# v53: v52 + attention tile loop layout: unmasked tiles fall through from the tile-type test into QK set-up and from the post-QK test into the softmax (flag logic and mask paths out of line)
# speedup vs baseline: 1.0172x; 1.0033x over previous
; template <int PM> DI void attn_phase(const Params& p, int l, char* smem, int* s_item, int wv, int cidx) {
;     ...
;         bool active = (PM != 1);
;         const int tpos = local_t0 + 64 * (i - nplain);
;         if (i >= nplain) {
;           if (mode == 1) active = (PM != 1) && (tpos + 63 >= tq0 - 128) && (tpos <= tq0 + 31 + 128);
;           else { const int dr = (tpos >> 6) - kr0; active = (PM != 1) && (dr >= 0 && dr < 8); }
;         }
.LBB0_430:
	s_cmp_ge_u32 s2, s80
	s_cselect_b64 s[0:1], -1, 0
	s_mov_b64 s[2:3], -1
	s_cbranch_scc1 .Lwf_431

; template <int PM> DI void attn_phase(const Params& p, int l, char* smem, int* s_item, int wv, int cidx) {
;     ...
;         if (active) {
;           if (i >= nplain) {
.LBB0_441:
	s_and_b64 vcc, exec, s[74:75]
	s_cbranch_vccnz .LBB0_515
	s_and_b64 vcc, exec, s[0:1]
	s_cbranch_vccnz .Lmp_443

; template <int PM> DI void attn_phase(const Params& p, int l, char* smem, int* s_item, int wv, int cidx) {
;     ...
;         if (i >= nplain) {
;           if (mode == 1) active = (PM != 1) && (tpos + 63 >= tq0 - 128) && (tpos <= tq0 + 31 + 128);
;           else { const int dr = (tpos >> 6) - kr0; active = (PM != 1) && (dr >= 0 && dr < 8); }
;         }
;     ...
;             } else {
;               const int kr = tpos >> 6;
;               const int rbase = (kr - qrow + 7) * 31 + (15 - qcol);
; #pragma unroll
;               for (int kb = 0; kb < 2; ++kb)
; #pragma unroll
;                 for (int e = 0; e < 16; ++e) {
;                   const int kidx = kb * 32 + (e & 3) + 8 * (e >> 2) + 4 * h;
;                   const int dc = kidx - cstart;
;                   const bool valid = dc >= 0 && dc < 16;
;                   const float bias = rpb_s[valid ? rbase + kidx : 0];
;                   sacc[kb][e] = valid ? sacc[kb][e] + bias : -1e30f;
;                 }
.Lwf_431:
	s_mov_b64 s[74:75], -1
	s_and_b64 vcc, exec, s[78:79]
	s_cbranch_vccz .LBB0_433
	s_ashr_i32 s2, s92, 6
	s_sub_i32 s2, s2, s83
	s_cmp_lt_u32 s2, 8
	s_mov_b64 s[74:75], 0
	s_cselect_b64 s[2:3], -1, 0
.LBB0_433:
	s_andn2_b64 vcc, exec, s[74:75]
	s_cbranch_vccnz .LBB0_435
	s_add_i32 s2, s92, 63
	s_cmp_ge_i32 s2, s87
	s_cselect_b64 s[2:3], -1, 0
	s_cmp_le_i32 s92, s88
	s_cselect_b64 s[74:75], -1, 0
	s_and_b64 s[2:3], s[2:3], s[74:75]
	s_branch .LBB0_435
.Lmp_443:
	s_mov_b64 s[0:1], -1
	s_and_b64 vcc, exec, s[78:79]
	s_cbranch_vccz .LBB0_509
	s_ashr_i32 s0, s92, 6
	s_sub_i32 s0, s0, s82
	s_mul_i32 s0, s0, 31
	v_sub_u32_e32 v0, s0, v205
	s_waitcnt lgkmcnt(2)
	v_lshl_add_u32 v2, v0, 2, v236
	v_lshl_add_u32 v0, v198, 2, v2
	v_lshl_add_u32 v3, v248, 2, v2
	v_lshl_add_u32 v4, v249, 2, v2
	v_lshl_add_u32 v5, v250, 2, v2
	ds_read_b32 v48, v0 offset:928
	ds_read_b32 v49, v0 offset:932
	ds_read_b32 v50, v0 offset:936
	ds_read_b32 v51, v0 offset:940
	ds_read_b32 v52, v0 offset:960
	ds_read_b32 v53, v0 offset:964
	ds_read_b32 v54, v0 offset:968
	ds_read_b32 v55, v0 offset:972
	ds_read_b32 v56, v0 offset:992
	ds_read_b32 v57, v0 offset:996
	ds_read_b32 v58, v0 offset:1000
	ds_read_b32 v59, v0 offset:1004
	ds_read_b32 v60, v0 offset:1024
	ds_read_b32 v61, v0 offset:1028
	ds_read_b32 v62, v0 offset:1032
	ds_read_b32 v63, v0 offset:1036
	ds_read_b32 v64, v0 offset:1056
	ds_read_b32 v65, v3 offset:1056
	ds_read_b32 v66, v4 offset:1056
	ds_read_b32 v67, v5 offset:1056
	ds_read_b32 v68, v0 offset:1088
	ds_read_b32 v69, v0 offset:1092
	ds_read_b32 v70, v0 offset:1096
	ds_read_b32 v71, v0 offset:1100
	ds_read_b32 v72, v0 offset:1120
	ds_read_b32 v73, v0 offset:1124
	ds_read_b32 v74, v0 offset:1128
	ds_read_b32 v75, v0 offset:1132
	ds_read_b32 v76, v0 offset:1152
	ds_read_b32 v77, v0 offset:1156
	ds_read_b32 v78, v0 offset:1160
	ds_read_b32 v79, v0 offset:1164
	s_waitcnt lgkmcnt(0)
	v_add_f32_e32 v48, v16, v48
	v_add_f32_e32 v49, v17, v49
	v_add_f32_e32 v50, v18, v50
	v_add_f32_e32 v51, v19, v51
	v_add_f32_e32 v52, v20, v52
	v_add_f32_e32 v53, v21, v53
	v_add_f32_e32 v54, v22, v54
	v_add_f32_e32 v55, v23, v55
	v_add_f32_e32 v56, v24, v56
	v_add_f32_e32 v57, v25, v57
	v_add_f32_e32 v58, v26, v58
	v_add_f32_e32 v59, v27, v59
	v_add_f32_e32 v60, v28, v60
	v_add_f32_e32 v61, v29, v61
	v_add_f32_e32 v62, v30, v62
	v_add_f32_e32 v63, v31, v63
	v_add_f32_e32 v64, v32, v64
	v_add_f32_e32 v65, v33, v65
	v_add_f32_e32 v66, v34, v66
	v_add_f32_e32 v67, v35, v67
	v_add_f32_e32 v68, v36, v68
	v_add_f32_e32 v69, v37, v69
	v_add_f32_e32 v70, v38, v70
	v_add_f32_e32 v71, v39, v71
	v_add_f32_e32 v72, v40, v72
	v_add_f32_e32 v73, v41, v73
	v_add_f32_e32 v74, v42, v74
	v_add_f32_e32 v75, v43, v75
	v_add_f32_e32 v76, v44, v76
	v_add_f32_e32 v77, v45, v77
	v_add_f32_e32 v78, v46, v78
	v_add_f32_e32 v79, v47, v79
	v_cndmask_b32_e64 v48, v237, v48, s[6:7]
	v_cndmask_b32_e64 v49, v237, v49, s[8:9]
	v_cndmask_b32_e64 v50, v237, v50, s[10:11]
	v_cndmask_b32_e64 v51, v237, v51, s[12:13]
	v_cndmask_b32_e64 v52, v237, v52, s[14:15]
	v_cndmask_b32_e64 v53, v237, v53, s[16:17]
	v_cndmask_b32_e64 v54, v237, v54, s[18:19]
	v_cndmask_b32_e64 v55, v237, v55, s[20:21]
	v_cndmask_b32_e64 v56, v237, v56, s[22:23]
	v_cndmask_b32_e64 v57, v237, v57, s[24:25]
	v_cndmask_b32_e64 v58, v237, v58, s[26:27]
	v_cndmask_b32_e64 v59, v237, v59, s[28:29]
	v_cndmask_b32_e64 v60, v237, v60, s[30:31]
	v_cndmask_b32_e64 v61, v237, v61, s[34:35]
	v_cndmask_b32_e64 v62, v237, v62, s[36:37]
	v_cndmask_b32_e64 v63, v237, v63, s[38:39]
	v_cndmask_b32_e64 v64, v237, v64, s[40:41]
	v_cndmask_b32_e64 v65, v237, v65, s[42:43]
	v_cndmask_b32_e64 v66, v237, v66, s[44:45]
	v_cndmask_b32_e64 v67, v237, v67, s[46:47]
	v_cndmask_b32_e64 v68, v237, v68, s[48:49]
	v_cndmask_b32_e64 v69, v237, v69, s[50:51]
	v_cndmask_b32_e64 v70, v237, v70, s[52:53]
	v_cndmask_b32_e64 v71, v237, v71, s[54:55]
	v_cndmask_b32_e64 v72, v237, v72, s[56:57]
	v_cndmask_b32_e64 v73, v237, v73, s[58:59]
	v_cndmask_b32_e64 v74, v237, v74, s[60:61]
	v_cndmask_b32_e64 v75, v237, v75, s[62:63]
	v_cndmask_b32_e64 v76, v237, v76, s[64:65]
	v_cndmask_b32_e64 v77, v237, v77, s[66:67]
	v_cndmask_b32_e64 v78, v237, v78, s[68:69]
	v_cndmask_b32_e64 v79, v237, v79, s[70:71]
	s_mov_b64 s[0:1], 0

; DI float half_max(float v) { const auto r = __builtin_amdgcn_permlane32_swap(__float_as_uint(v), __float_as_uint(v), false, false); return fmaxf(__uint_as_float(r[0]), __uint_as_float(r[1])); }
; template <int PM> DI void attn_phase(const Params& p, int l, char* smem, int* s_item, int wv, int cidx) {
;     ...
;                   const float bias = rpb_s[valid ? rbase + kidx : 0];
;                   sacc[kb][e] = valid ? sacc[kb][e] + bias : -1e30f;
;                 }
;             }
;           }
;           float mt = sacc[0][0];
; #pragma unroll
;           for (int e = 1; e < 16; ++e) mt = fmaxf(mt, sacc[0][e]);
; #pragma unroll
;           for (int e = 0; e < 16; ++e) mt = fmaxf(mt, sacc[1][e]);
;           mt = half_max(mt);
.LBB0_511:
	s_waitcnt lgkmcnt(5)
	v_mov_b64_e32 v[16:17], v[48:49]
	v_mov_b64_e32 v[18:19], v[50:51]
	v_mov_b64_e32 v[20:21], v[52:53]
	v_mov_b64_e32 v[22:23], v[54:55]
	v_mov_b64_e32 v[24:25], v[56:57]
	v_mov_b64_e32 v[26:27], v[58:59]
	v_mov_b64_e32 v[28:29], v[60:61]
	v_mov_b64_e32 v[30:31], v[62:63]
	v_mov_b64_e32 v[32:33], v[64:65]
	v_mov_b64_e32 v[34:35], v[66:67]
	v_mov_b64_e32 v[36:37], v[68:69]
	v_mov_b64_e32 v[38:39], v[70:71]
	v_mov_b64_e32 v[40:41], v[72:73]
	v_mov_b64_e32 v[42:43], v[74:75]
	v_mov_b64_e32 v[44:45], v[76:77]
	v_mov_b64_e32 v[46:47], v[78:79]
	s_branch .LBB0_512
